# FFN-up mainloop LDS-DMA: SGPR base + 32-bit VGPR offset addressing, the 16 per-iteration v_lshl_add_u64 removed
# speedup vs baseline: 1.0077x; 1.0013x over previous
; #define PG8_STAGE(bufoff, gbase, voff) do { _Pragma("unroll") for (int _i = 0; _i < 2; ++_i) \
;         __builtin_amdgcn_global_load_lds((const unsigned*)((const char*)(gbase) + (voff)[_i]), (LAS unsigned*)(lds + (bufoff) + ldsw + _i * 8192), 16, 0, 0); } while (0)
; #define PG8_LDA(dst, b, h) do { _Pragma("unroll") for (int m = 0; m < 4; ++m) _Pragma("unroll") for (int k = 0; k < 2; ++k) dst[m][k] = *(const LAS bf16x8*)(lds + PG8_SA(b, h) + aoff + m * 2048 + k * 1024); } while (0)
; #define PG8_LDB(dst, b, h) do { _Pragma("unroll") for (int n = 0; n < 2; ++n) _Pragma("unroll") for (int k = 0; k < 2; ++k) dst[n][k] = *(const LAS bf16x8*)(lds + PG8_SB(b, h) + boff + n * 2048 + k * 1024); } while (0)
; #define PG8_MMA(ai, bj, At, Bt) do { __builtin_amdgcn_s_setprio(1); _Pragma("unroll") for (int m = 0; m < 4; ++m) _Pragma("unroll") for (int n = 0; n < 2; ++n) _Pragma("unroll") for (int k = 0; k < 2; ++k) \
;         acc[ai][bj][m][n] = __builtin_amdgcn_mfma_f32_16x16x32_bf16(Bt[n][k], At[m][k], acc[ai][bj][m][n], 0, 0, 0); __builtin_amdgcn_s_setprio(0); } while (0)
; #define PG8_WAIT_V(n) asm volatile("s_waitcnt vmcnt(" #n ")" ::: "memory")
; #define PG8_WAIT_L(n) asm volatile("s_waitcnt lgkmcnt(" #n ")" ::: "memory")
; #define PG8_BAR __builtin_amdgcn_s_barrier()
; #define PG8_SCHED __builtin_amdgcn_sched_barrier(0)
; template <class Epi, class Sched>
; __device__ __forceinline__ void gemm_phase(LAS unsigned char* lds, const int lda, const int ldb, const int K, const Sched& S, const Epi& E, int tid) {
;     ...
;         for (int t = 0; t < nt; t += 2) {
;             const bool last = (t == nt - 2);
;             const char* a1 = cA + (size_t)(t + 1) * kstep;
;             const char* a2 = last ? nA : cA + (size_t)(t + 2) * kstep; const char* b2 = last ? nB : cB + (size_t)(t + 2) * kstep;
;             const char* a3 = a2 + kstep; const char* b3 = b2 + kstep;
;             PG8_LDB(B0, 0, 0); PG8_LDB(B1, 0, 1); PG8_SCHED; PG8_LDA(At, 0, 0); PG8_STAGE(PG8_SA(1, 1), a1 + hA, voffA);
;             PG8_WAIT_V(8); PG8_WAIT_L(0); PG8_BAR; PG8_MMA(0, 0, At, B0); PG8_MMA(0, 1, At, B1); PG8_BAR; PG8_SCHED;
;             PG8_LDA(At, 0, 1); PG8_STAGE(PG8_SB(0, 0), b2, voffB); PG8_STAGE(PG8_SB(0, 1), b2 + hB, voffB); PG8_STAGE(PG8_SA(0, 0), a2, voffA);
;             PG8_WAIT_V(8); PG8_WAIT_L(0); PG8_BAR; PG8_MMA(1, 0, At, B0); PG8_MMA(1, 1, At, B1); PG8_BAR; PG8_SCHED;
.LBB0_681:
	s_add_u32 s26, s56, 0xfff80080
	s_addc_u32 s27, s57, -1
	s_add_i32 s34, 0, 0x10000
	s_cmp_eq_u32 s60, 28
	s_cselect_b32 vcc_hi, s9, s27
	s_cselect_b32 vcc_lo, s8, s26
	v_add_u32_e32 v0, s34, v198
	s_cselect_b32 s27, s11, s19
	s_cselect_b32 s26, s10, s17
	s_add_i32 s76, 0, 0x14000
	ds_read_b128 v[114:117], v0
	ds_read_b128 v[118:121], v0 offset:1024
	ds_read_b128 v[122:125], v0 offset:2048
	ds_read_b128 v[126:129], v0 offset:3072
	v_add_u32_e32 v0, s76, v198
	ds_read_b128 v[130:133], v0
	ds_read_b128 v[134:137], v0 offset:1024
	ds_read_b128 v[138:141], v0 offset:2048
	ds_read_b128 v[142:145], v0 offset:3072
	s_add_i32 m0, s29, 0xc000
	ds_read_b128 v[162:165], v237
	ds_read_b128 v[166:169], v237 offset:1024
	ds_read_b128 v[202:205], v237 offset:2048
	ds_read_b128 v[206:209], v237 offset:3072
	ds_read_b128 v[210:213], v237 offset:4096
	ds_read_b128 v[214:217], v237 offset:5120
	ds_read_b128 v[218:221], v237 offset:6144
	ds_read_b128 v[240:243], v237 offset:7168
	global_load_lds_dwordx4 v196, s[56:57]
	s_add_i32 m0, s29, 0xe000
	s_nop 0
	global_load_lds_dwordx4 v200, s[56:57]
	s_waitcnt vmcnt(8)
	s_waitcnt lgkmcnt(0)
	s_barrier
	s_setprio 1
	s_waitcnt lgkmcnt(0)
	v_mfma_f32_16x16x32_bf16 v[158:161], v[114:117], v[162:165], v[158:161]
	v_mfma_f32_16x16x32_bf16 v[62:65], v[122:125], v[162:165], v[62:65]
	v_mfma_f32_16x16x32_bf16 v[150:153], v[114:117], v[202:205], v[150:153]
	v_mfma_f32_16x16x32_bf16 v[54:57], v[122:125], v[202:205], v[54:57]
	v_mfma_f32_16x16x32_bf16 v[110:113], v[114:117], v[210:213], v[110:113]
	v_mfma_f32_16x16x32_bf16 v[46:49], v[122:125], v[210:213], v[46:49]
	v_mfma_f32_16x16x32_bf16 v[102:105], v[114:117], v[218:221], v[102:105]
	v_mfma_f32_16x16x32_bf16 v[38:41], v[122:125], v[218:221], v[38:41]
	v_mfma_f32_16x16x32_bf16 v[158:161], v[118:121], v[166:169], v[158:161]
	v_mfma_f32_16x16x32_bf16 v[62:65], v[126:129], v[166:169], v[62:65]
	v_mfma_f32_16x16x32_bf16 v[150:153], v[118:121], v[206:209], v[150:153]
	v_mfma_f32_16x16x32_bf16 v[54:57], v[126:129], v[206:209], v[54:57]
	v_mfma_f32_16x16x32_bf16 v[110:113], v[118:121], v[214:217], v[110:113]
	v_mfma_f32_16x16x32_bf16 v[46:49], v[126:129], v[214:217], v[46:49]
	v_mfma_f32_16x16x32_bf16 v[102:105], v[118:121], v[240:243], v[102:105]
	v_mfma_f32_16x16x32_bf16 v[38:41], v[126:129], v[240:243], v[38:41]
	s_setprio 0
	s_setprio 1
	v_mfma_f32_16x16x32_bf16 v[154:157], v[130:133], v[162:165], v[154:157]
	v_mfma_f32_16x16x32_bf16 v[58:61], v[138:141], v[162:165], v[58:61]
	v_mfma_f32_16x16x32_bf16 v[146:149], v[130:133], v[202:205], v[146:149]
	v_mfma_f32_16x16x32_bf16 v[50:53], v[138:141], v[202:205], v[50:53]
	v_mfma_f32_16x16x32_bf16 v[106:109], v[130:133], v[210:213], v[106:109]
	v_mfma_f32_16x16x32_bf16 v[42:45], v[138:141], v[210:213], v[42:45]
	v_mfma_f32_16x16x32_bf16 v[98:101], v[130:133], v[218:221], v[98:101]
	v_mfma_f32_16x16x32_bf16 v[34:37], v[138:141], v[218:221], v[34:37]
	v_mfma_f32_16x16x32_bf16 v[154:157], v[134:137], v[166:169], v[154:157]
	v_mfma_f32_16x16x32_bf16 v[58:61], v[142:145], v[166:169], v[58:61]
	v_mfma_f32_16x16x32_bf16 v[146:149], v[134:137], v[206:209], v[146:149]
	v_mfma_f32_16x16x32_bf16 v[50:53], v[142:145], v[206:209], v[50:53]
	v_mfma_f32_16x16x32_bf16 v[106:109], v[134:137], v[214:217], v[106:109]
	v_mfma_f32_16x16x32_bf16 v[42:45], v[142:145], v[214:217], v[42:45]
	v_mfma_f32_16x16x32_bf16 v[98:101], v[134:137], v[240:243], v[98:101]
	v_mfma_f32_16x16x32_bf16 v[34:37], v[142:145], v[240:243], v[34:37]
	s_setprio 0
	s_barrier
	s_add_i32 s34, s34, s28
	s_mov_b32 m0, s34
	ds_read_b128 v[162:165], v237 offset:16384
	ds_read_b128 v[166:169], v237 offset:17408
	ds_read_b128 v[202:205], v237 offset:18432
	ds_read_b128 v[206:209], v237 offset:19456
	ds_read_b128 v[210:213], v237 offset:20480
	ds_read_b128 v[214:217], v237 offset:21504
	ds_read_b128 v[218:221], v237 offset:22528
	ds_read_b128 v[240:243], v237 offset:23552
	global_load_lds_dwordx4 v172, s[26:27]
	s_add_i32 m0, s34, 0x2000
	s_add_u32 s34, s26, 0x80000
	s_addc_u32 s35, s27, 0
	s_add_i32 s76, s76, s28
	global_load_lds_dwordx4 v176, s[26:27]
	s_mov_b32 m0, s76
	s_nop 0
	global_load_lds_dwordx4 v172, s[34:35]
	s_add_i32 m0, s76, 0x2000
	s_nop 0
	global_load_lds_dwordx4 v176, s[34:35]
	s_mov_b32 m0, s29
	s_nop 0
	global_load_lds_dwordx4 v170, vcc
	s_mov_b32 m0, s67
	s_nop 0
	global_load_lds_dwordx4 v174, vcc
	s_waitcnt vmcnt(8)
	s_waitcnt lgkmcnt(0)
	s_barrier
	s_setprio 1
	s_waitcnt lgkmcnt(0)
	v_mfma_f32_16x16x32_bf16 v[94:97], v[114:117], v[162:165], v[94:97]
	v_mfma_f32_16x16x32_bf16 v[30:33], v[122:125], v[162:165], v[30:33]
	v_mfma_f32_16x16x32_bf16 v[86:89], v[114:117], v[202:205], v[86:89]
	v_mfma_f32_16x16x32_bf16 v[22:25], v[122:125], v[202:205], v[22:25]
	v_mfma_f32_16x16x32_bf16 v[78:81], v[114:117], v[210:213], v[78:81]
	v_mfma_f32_16x16x32_bf16 v[14:17], v[122:125], v[210:213], v[14:17]
	v_mfma_f32_16x16x32_bf16 v[70:73], v[114:117], v[218:221], v[70:73]
	v_mfma_f32_16x16x32_bf16 v[6:9], v[122:125], v[218:221], v[6:9]
	v_mfma_f32_16x16x32_bf16 v[94:97], v[118:121], v[166:169], v[94:97]
	v_mfma_f32_16x16x32_bf16 v[30:33], v[126:129], v[166:169], v[30:33]
	v_mfma_f32_16x16x32_bf16 v[86:89], v[118:121], v[206:209], v[86:89]
	v_mfma_f32_16x16x32_bf16 v[22:25], v[126:129], v[206:209], v[22:25]
	v_mfma_f32_16x16x32_bf16 v[78:81], v[118:121], v[214:217], v[78:81]
	v_mfma_f32_16x16x32_bf16 v[14:17], v[126:129], v[214:217], v[14:17]
	v_mfma_f32_16x16x32_bf16 v[70:73], v[118:121], v[240:243], v[70:73]
	v_mfma_f32_16x16x32_bf16 v[6:9], v[126:129], v[240:243], v[6:9]
	s_setprio 0
	s_setprio 1
	v_mfma_f32_16x16x32_bf16 v[90:93], v[130:133], v[162:165], v[90:93]
	v_mfma_f32_16x16x32_bf16 v[26:29], v[138:141], v[162:165], v[26:29]
	v_mfma_f32_16x16x32_bf16 v[82:85], v[130:133], v[202:205], v[82:85]
	v_mfma_f32_16x16x32_bf16 v[18:21], v[138:141], v[202:205], v[18:21]
	v_mfma_f32_16x16x32_bf16 v[74:77], v[130:133], v[210:213], v[74:77]
	v_mfma_f32_16x16x32_bf16 v[10:13], v[138:141], v[210:213], v[10:13]
	v_mfma_f32_16x16x32_bf16 v[66:69], v[130:133], v[218:221], v[66:69]
	v_mfma_f32_16x16x32_bf16 v[2:5], v[138:141], v[218:221], v[2:5]
	v_mfma_f32_16x16x32_bf16 v[90:93], v[134:137], v[166:169], v[90:93]
	v_mfma_f32_16x16x32_bf16 v[26:29], v[142:145], v[166:169], v[26:29]
	v_mfma_f32_16x16x32_bf16 v[82:85], v[134:137], v[206:209], v[82:85]
	v_mfma_f32_16x16x32_bf16 v[18:21], v[142:145], v[206:209], v[18:21]
	v_mfma_f32_16x16x32_bf16 v[74:77], v[134:137], v[214:217], v[74:77]
	v_mfma_f32_16x16x32_bf16 v[10:13], v[142:145], v[214:217], v[10:13]
	v_mfma_f32_16x16x32_bf16 v[66:69], v[134:137], v[240:243], v[66:69]
	v_mfma_f32_16x16x32_bf16 v[2:5], v[142:145], v[240:243], v[2:5]
	s_setprio 0
	s_barrier
; #define PG8_STAGE(bufoff, gbase, voff) do { _Pragma("unroll") for (int _i = 0; _i < 2; ++_i) \
;         __builtin_amdgcn_global_load_lds((const unsigned*)((const char*)(gbase) + (voff)[_i]), (LAS unsigned*)(lds + (bufoff) + ldsw + _i * 8192), 16, 0, 0); } while (0)
; #define PG8_LDA(dst, b, h) do { _Pragma("unroll") for (int m = 0; m < 4; ++m) _Pragma("unroll") for (int k = 0; k < 2; ++k) dst[m][k] = *(const LAS bf16x8*)(lds + PG8_SA(b, h) + aoff + m * 2048 + k * 1024); } while (0)
; #define PG8_LDB(dst, b, h) do { _Pragma("unroll") for (int n = 0; n < 2; ++n) _Pragma("unroll") for (int k = 0; k < 2; ++k) dst[n][k] = *(const LAS bf16x8*)(lds + PG8_SB(b, h) + boff + n * 2048 + k * 1024); } while (0)
; #define PG8_MMA(ai, bj, At, Bt) do { __builtin_amdgcn_s_setprio(1); _Pragma("unroll") for (int m = 0; m < 4; ++m) _Pragma("unroll") for (int n = 0; n < 2; ++n) _Pragma("unroll") for (int k = 0; k < 2; ++k) \
;         acc[ai][bj][m][n] = __builtin_amdgcn_mfma_f32_16x16x32_bf16(Bt[n][k], At[m][k], acc[ai][bj][m][n], 0, 0, 0); __builtin_amdgcn_s_setprio(0); } while (0)
; #define PG8_WAIT_V(n) asm volatile("s_waitcnt vmcnt(" #n ")" ::: "memory")
; #define PG8_WAIT_L(n) asm volatile("s_waitcnt lgkmcnt(" #n ")" ::: "memory")
; #define PG8_BAR __builtin_amdgcn_s_barrier()
; #define PG8_SCHED __builtin_amdgcn_sched_barrier(0)
; template <class Epi, class Sched>
; __device__ __forceinline__ void gemm_phase(LAS unsigned char* lds, const int lda, const int ldb, const int K, const Sched& S, const Epi& E, int tid) {
;     ...
;             PG8_LDB(B0, 1, 0); PG8_LDB(B1, 1, 1); PG8_SCHED; PG8_LDA(At, 1, 0); PG8_STAGE(PG8_SA(0, 1), a2 + hA, voffA);
;             PG8_WAIT_V(8); PG8_WAIT_L(0); PG8_BAR; PG8_MMA(0, 0, At, B0); PG8_MMA(0, 1, At, B1); PG8_BAR; PG8_SCHED;
;             PG8_LDA(At, 1, 1); PG8_STAGE(PG8_SB(1, 0), b3, voffB); PG8_STAGE(PG8_SB(1, 1), b3 + hB, voffB); PG8_STAGE(PG8_SA(1, 0), a3, voffA);
;             PG8_WAIT_V(8); PG8_WAIT_L(0); PG8_BAR; PG8_MMA(1, 0, At, B0); PG8_MMA(1, 1, At, B1); PG8_BAR; PG8_SCHED;
;         }
	s_add_i32 s76, 0, 0x18000
	v_add_u32_e32 v0, s76, v198
	s_add_i32 s94, 0, 0x1c000
	ds_read_b128 v[114:117], v0
	ds_read_b128 v[118:121], v0 offset:1024
	ds_read_b128 v[122:125], v0 offset:2048
	ds_read_b128 v[126:129], v0 offset:3072
	v_add_u32_e32 v0, s94, v198
	ds_read_b128 v[130:133], v0
	ds_read_b128 v[134:137], v0 offset:1024
	ds_read_b128 v[138:141], v0 offset:2048
	ds_read_b128 v[142:145], v0 offset:3072
	s_add_u32 s34, vcc_lo, 0x80000
	s_addc_u32 s35, vcc_hi, 0
	s_mov_b32 m0, s25
	ds_read_b128 v[162:165], v237 offset:32768
	ds_read_b128 v[166:169], v237 offset:33792
	ds_read_b128 v[202:205], v237 offset:34816
	ds_read_b128 v[206:209], v237 offset:35840
	ds_read_b128 v[210:213], v237 offset:36864
	ds_read_b128 v[214:217], v237 offset:37888
	ds_read_b128 v[218:221], v237 offset:38912
	ds_read_b128 v[240:243], v237 offset:39936
	global_load_lds_dwordx4 v170, s[34:35]
	s_mov_b32 m0, s0
	s_nop 0
	global_load_lds_dwordx4 v174, s[34:35]
	s_waitcnt vmcnt(8)
	s_waitcnt lgkmcnt(0)
	s_barrier
	s_setprio 1
	s_waitcnt lgkmcnt(0)
	v_mfma_f32_16x16x32_bf16 v[158:161], v[114:117], v[162:165], v[158:161]
	v_mfma_f32_16x16x32_bf16 v[62:65], v[122:125], v[162:165], v[62:65]
	v_mfma_f32_16x16x32_bf16 v[150:153], v[114:117], v[202:205], v[150:153]
	v_mfma_f32_16x16x32_bf16 v[54:57], v[122:125], v[202:205], v[54:57]
	v_mfma_f32_16x16x32_bf16 v[110:113], v[114:117], v[210:213], v[110:113]
	v_mfma_f32_16x16x32_bf16 v[46:49], v[122:125], v[210:213], v[46:49]
	v_mfma_f32_16x16x32_bf16 v[102:105], v[114:117], v[218:221], v[102:105]
	v_mfma_f32_16x16x32_bf16 v[38:41], v[122:125], v[218:221], v[38:41]
	v_mfma_f32_16x16x32_bf16 v[158:161], v[118:121], v[166:169], v[158:161]
	v_mfma_f32_16x16x32_bf16 v[62:65], v[126:129], v[166:169], v[62:65]
	v_mfma_f32_16x16x32_bf16 v[150:153], v[118:121], v[206:209], v[150:153]
	v_mfma_f32_16x16x32_bf16 v[54:57], v[126:129], v[206:209], v[54:57]
	v_mfma_f32_16x16x32_bf16 v[110:113], v[118:121], v[214:217], v[110:113]
	v_mfma_f32_16x16x32_bf16 v[46:49], v[126:129], v[214:217], v[46:49]
	v_mfma_f32_16x16x32_bf16 v[102:105], v[118:121], v[240:243], v[102:105]
	v_mfma_f32_16x16x32_bf16 v[38:41], v[126:129], v[240:243], v[38:41]
	s_setprio 0
	s_setprio 1
	v_mfma_f32_16x16x32_bf16 v[154:157], v[130:133], v[162:165], v[154:157]
	v_mfma_f32_16x16x32_bf16 v[58:61], v[138:141], v[162:165], v[58:61]
	v_mfma_f32_16x16x32_bf16 v[146:149], v[130:133], v[202:205], v[146:149]
	v_mfma_f32_16x16x32_bf16 v[50:53], v[138:141], v[202:205], v[50:53]
	v_mfma_f32_16x16x32_bf16 v[106:109], v[130:133], v[210:213], v[106:109]
	v_mfma_f32_16x16x32_bf16 v[42:45], v[138:141], v[210:213], v[42:45]
	v_mfma_f32_16x16x32_bf16 v[98:101], v[130:133], v[218:221], v[98:101]
	v_mfma_f32_16x16x32_bf16 v[34:37], v[138:141], v[218:221], v[34:37]
	v_mfma_f32_16x16x32_bf16 v[154:157], v[134:137], v[166:169], v[154:157]
	v_mfma_f32_16x16x32_bf16 v[58:61], v[142:145], v[166:169], v[58:61]
	v_mfma_f32_16x16x32_bf16 v[146:149], v[134:137], v[206:209], v[146:149]
	v_mfma_f32_16x16x32_bf16 v[50:53], v[142:145], v[206:209], v[50:53]
	v_mfma_f32_16x16x32_bf16 v[106:109], v[134:137], v[214:217], v[106:109]
	v_mfma_f32_16x16x32_bf16 v[42:45], v[142:145], v[214:217], v[42:45]
	v_mfma_f32_16x16x32_bf16 v[98:101], v[134:137], v[240:243], v[98:101]
	v_mfma_f32_16x16x32_bf16 v[34:37], v[142:145], v[240:243], v[34:37]
	s_setprio 0
	s_barrier
	s_add_i32 s34, s76, s28
	s_add_u32 s98, s26, s30
	s_addc_u32 s99, s27, s31
	s_mov_b32 m0, s34
	ds_read_b128 v[162:165], v237 offset:49152
	ds_read_b128 v[166:169], v237 offset:50176
	ds_read_b128 v[202:205], v237 offset:51200
	ds_read_b128 v[206:209], v237 offset:52224
	ds_read_b128 v[210:213], v237 offset:53248
	ds_read_b128 v[214:217], v237 offset:54272
	ds_read_b128 v[218:221], v237 offset:55296
	ds_read_b128 v[240:243], v237 offset:56320
	global_load_lds_dwordx4 v172, s[98:99]
	s_add_i32 m0, s34, 0x2000
	s_add_u32 s26, s26, 0x80080
	s_addc_u32 s27, s27, 0
	s_add_i32 s34, s94, s28
	global_load_lds_dwordx4 v176, s[98:99]
	s_mov_b32 m0, s34
	s_nop 0
	global_load_lds_dwordx4 v172, s[26:27]
	s_add_i32 m0, s34, 0x2000
	s_nop 0
	global_load_lds_dwordx4 v176, s[26:27]
	s_add_u32 s100, vcc_lo, s30
	s_addc_u32 s101, vcc_hi, s31
	s_mov_b32 m0, s22
	s_nop 0
	global_load_lds_dwordx4 v170, s[100:101]
	s_mov_b32 m0, s23
	s_nop 0
	global_load_lds_dwordx4 v174, s[100:101]
	s_waitcnt vmcnt(8)
	s_waitcnt lgkmcnt(0)
	s_barrier
	s_setprio 1
	s_waitcnt lgkmcnt(0)
	v_mfma_f32_16x16x32_bf16 v[94:97], v[114:117], v[162:165], v[94:97]
	v_mfma_f32_16x16x32_bf16 v[30:33], v[122:125], v[162:165], v[30:33]
	v_mfma_f32_16x16x32_bf16 v[86:89], v[114:117], v[202:205], v[86:89]
	v_mfma_f32_16x16x32_bf16 v[22:25], v[122:125], v[202:205], v[22:25]
	v_mfma_f32_16x16x32_bf16 v[78:81], v[114:117], v[210:213], v[78:81]
	v_mfma_f32_16x16x32_bf16 v[14:17], v[122:125], v[210:213], v[14:17]
	v_mfma_f32_16x16x32_bf16 v[70:73], v[114:117], v[218:221], v[70:73]
	v_mfma_f32_16x16x32_bf16 v[6:9], v[122:125], v[218:221], v[6:9]
	v_mfma_f32_16x16x32_bf16 v[94:97], v[118:121], v[166:169], v[94:97]
	v_mfma_f32_16x16x32_bf16 v[30:33], v[126:129], v[166:169], v[30:33]
	v_mfma_f32_16x16x32_bf16 v[86:89], v[118:121], v[206:209], v[86:89]
	v_mfma_f32_16x16x32_bf16 v[22:25], v[126:129], v[206:209], v[22:25]
	v_mfma_f32_16x16x32_bf16 v[78:81], v[118:121], v[214:217], v[78:81]
	v_mfma_f32_16x16x32_bf16 v[14:17], v[126:129], v[214:217], v[14:17]
	v_mfma_f32_16x16x32_bf16 v[70:73], v[118:121], v[240:243], v[70:73]
	v_mfma_f32_16x16x32_bf16 v[6:9], v[126:129], v[240:243], v[6:9]
	s_setprio 0
	s_setprio 1
	v_mfma_f32_16x16x32_bf16 v[90:93], v[130:133], v[162:165], v[90:93]
	v_mfma_f32_16x16x32_bf16 v[26:29], v[138:141], v[162:165], v[26:29]
	v_mfma_f32_16x16x32_bf16 v[82:85], v[130:133], v[202:205], v[82:85]
	v_mfma_f32_16x16x32_bf16 v[18:21], v[138:141], v[202:205], v[18:21]
	v_mfma_f32_16x16x32_bf16 v[74:77], v[130:133], v[210:213], v[74:77]
	v_mfma_f32_16x16x32_bf16 v[10:13], v[138:141], v[210:213], v[10:13]
	v_mfma_f32_16x16x32_bf16 v[66:69], v[130:133], v[218:221], v[66:69]
	v_mfma_f32_16x16x32_bf16 v[2:5], v[138:141], v[218:221], v[2:5]
	v_mfma_f32_16x16x32_bf16 v[90:93], v[134:137], v[166:169], v[90:93]
	v_mfma_f32_16x16x32_bf16 v[26:29], v[142:145], v[166:169], v[26:29]
	v_mfma_f32_16x16x32_bf16 v[82:85], v[134:137], v[206:209], v[82:85]
	v_mfma_f32_16x16x32_bf16 v[18:21], v[142:145], v[206:209], v[18:21]
	v_mfma_f32_16x16x32_bf16 v[74:77], v[134:137], v[214:217], v[74:77]
	v_mfma_f32_16x16x32_bf16 v[10:13], v[142:145], v[214:217], v[10:13]
	v_mfma_f32_16x16x32_bf16 v[66:69], v[134:137], v[240:243], v[66:69]
	v_mfma_f32_16x16x32_bf16 v[2:5], v[142:145], v[240:243], v[2:5]
	s_setprio 0
	s_barrier
	s_add_i32 s60, s60, 2
	s_add_u32 s56, s56, 0x100
	s_addc_u32 s57, s57, 0
	s_add_u32 s17, s17, 0x100
	s_addc_u32 s19, s19, 0
	s_cmp_gt_u32 s60, 29
	s_cbranch_scc0 .LBB0_681
	s_and_b64 vcc, exec, s[90:91]
	s_cbranch_vccz .LBB0_686
	s_barrier
	s_and_saveexec_b64 s[26:27], s[40:41]
	s_movk_i32 s60, 0x2c00
	s_cbranch_execnz .LBB0_687

; __global__ void __launch_bounds__(512) mega_fwd(Params p) {
	.amdhsa_kernel _Z8mega_fwd6Params
		.amdhsa_group_segment_fixed_size 0
		.amdhsa_private_segment_fixed_size 0
		.amdhsa_kernarg_size 448
		.amdhsa_user_sgpr_count 2
		.amdhsa_user_sgpr_dispatch_ptr 0
		.amdhsa_user_sgpr_queue_ptr 0
		.amdhsa_user_sgpr_kernarg_segment_ptr 1
		.amdhsa_user_sgpr_dispatch_id 0
		.amdhsa_user_sgpr_kernarg_preload_length 0
		.amdhsa_user_sgpr_kernarg_preload_offset 0
		.amdhsa_user_sgpr_private_segment_size 0
		.amdhsa_uses_dynamic_stack 0
		.amdhsa_enable_private_segment 0
		.amdhsa_system_sgpr_workgroup_id_x 1
		.amdhsa_system_sgpr_workgroup_id_y 0
		.amdhsa_system_sgpr_workgroup_id_z 0
		.amdhsa_system_sgpr_workgroup_info 0
		.amdhsa_system_vgpr_workitem_id 2
		.amdhsa_next_free_vgpr 256
		.amdhsa_next_free_sgpr 102
		.amdhsa_accum_offset 256
		.amdhsa_reserve_vcc 1
		.amdhsa_float_round_mode_32 0
		.amdhsa_float_round_mode_16_64 0
		.amdhsa_float_denorm_mode_32 3
		.amdhsa_float_denorm_mode_16_64 3
		.amdhsa_dx10_clamp 1
		.amdhsa_ieee_mode 1
		.amdhsa_fp16_overflow 0
		.amdhsa_tg_split 0
		.amdhsa_exception_fp_ieee_invalid_op 0
		.amdhsa_exception_fp_denorm_src 0
		.amdhsa_exception_fp_ieee_div_zero 0
		.amdhsa_exception_fp_ieee_overflow 0
		.amdhsa_exception_fp_ieee_underflow 0
		.amdhsa_exception_fp_ieee_inexact 0
		.amdhsa_exception_int_div_zero 0
	.end_amdhsa_kernel

; __global__ void __launch_bounds__(512) mega_fwd(Params p) {
amdhsa.kernels:
  - .agpr_count:     0
    .args:
      - .offset:         0
        .size:           192
        .value_kind:     by_value
      - .offset:         192
        .size:           4
        .value_kind:     hidden_block_count_x
      - .offset:         196
        .size:           4
        .value_kind:     hidden_block_count_y
      - .offset:         200
        .size:           4
        .value_kind:     hidden_block_count_z
      - .offset:         204
        .size:           2
        .value_kind:     hidden_group_size_x
      - .offset:         206
        .size:           2
        .value_kind:     hidden_group_size_y
      - .offset:         208
        .size:           2
        .value_kind:     hidden_group_size_z
      - .offset:         210
        .size:           2
        .value_kind:     hidden_remainder_x
      - .offset:         212
        .size:           2
        .value_kind:     hidden_remainder_y
      - .offset:         214
        .size:           2
        .value_kind:     hidden_remainder_z
      - .offset:         232
        .size:           8
        .value_kind:     hidden_global_offset_x
      - .offset:         240
        .size:           8
        .value_kind:     hidden_global_offset_y
      - .offset:         248
        .size:           8
        .value_kind:     hidden_global_offset_z
      - .offset:         256
        .size:           2
        .value_kind:     hidden_grid_dims
      - .offset:         280
        .size:           8
        .value_kind:     hidden_multigrid_sync_arg
      - .offset:         312
        .size:           4
        .value_kind:     hidden_dynamic_lds_size
    .group_segment_fixed_size: 0
    .kernarg_segment_align: 8
    .kernarg_segment_size: 448
    .language:       OpenCL C
    .language_version:
      - 2
      - 0
    .max_flat_workgroup_size: 512
    .name:           _Z8mega_fwd6Params
    .private_segment_fixed_size: 0
    .sgpr_count:     108
    .sgpr_spill_count: 229
    .symbol:         _Z8mega_fwd6Params.kd
    .uniform_work_group_size: 1
    .uses_dynamic_stack: false
    .vgpr_count:     256
    .vgpr_spill_count: 0
    .wavefront_size: 64
